# GQA steady loop: loop-carried counter / DMA-address updates moved from after the loop-back barrier to before it (sec 7.11 back-edge trimming), on top of v42
# baseline (speedup 1.0000x reference)
.LBB0_513:
	s_waitcnt lgkmcnt(14)
	v_mfma_f32_32x32x16_bf16 v[2:17], v[134:137], v[150:153], v[2:17]
	v_exp_f32_e32 v66, v66
	v_exp_f32_e32 v67, v67
	v_exp_f32_e32 v68, v68
	v_exp_f32_e32 v69, v69
	s_waitcnt lgkmcnt(12)
	v_mfma_f32_32x32x16_bf16 v[18:33], v[134:137], v[146:149], v[18:33]
	v_exp_f32_e32 v70, v70
	v_exp_f32_e32 v71, v71
	v_exp_f32_e32 v72, v72
	v_exp_f32_e32 v73, v73
	v_add_u32_e32 v94, s13, v222
	ds_read_b128 v[174:177], v94
	ds_read_b128 v[170:173], v94 offset:512
	s_waitcnt lgkmcnt(12)
	v_mfma_f32_32x32x16_bf16 v[2:17], v[126:129], v[98:101], v[2:17]
	v_exp_f32_e32 v74, v74
	v_exp_f32_e32 v75, v75
	v_exp_f32_e32 v76, v76
	v_exp_f32_e32 v77, v77
	ds_read_b128 v[166:169], v94 offset:2048
	ds_read_b128 v[162:165], v94 offset:2560
	s_waitcnt lgkmcnt(12)
	v_mfma_f32_32x32x16_bf16 v[18:33], v[126:129], v[102:105], v[18:33]
	v_exp_f32_e32 v78, v78
	v_exp_f32_e32 v79, v79
	v_exp_f32_e32 v80, v80
	v_exp_f32_e32 v81, v81
	ds_read_b128 v[158:161], v94 offset:4096
	ds_read_b128 v[154:157], v94 offset:4608
	s_waitcnt lgkmcnt(12)
	v_mfma_f32_32x32x16_bf16 v[2:17], v[118:121], v[106:109], v[2:17]
	v_exp_f32_e32 v50, v50
	v_exp_f32_e32 v51, v51
	v_exp_f32_e32 v52, v52
	v_exp_f32_e32 v53, v53
	ds_read_b128 v[150:153], v94 offset:6144
	ds_read_b128 v[146:149], v94 offset:6656
	s_waitcnt lgkmcnt(12)
	v_mfma_f32_32x32x16_bf16 v[18:33], v[118:121], v[82:85], v[18:33]
	v_exp_f32_e32 v54, v54
	v_exp_f32_e32 v55, v55
	v_exp_f32_e32 v56, v56
	v_exp_f32_e32 v57, v57
	s_waitcnt lgkmcnt(10)
	v_mfma_f32_32x32x16_bf16 v[2:17], v[114:117], v[86:89], v[2:17]
	v_exp_f32_e32 v58, v58
	v_exp_f32_e32 v59, v59
	v_exp_f32_e32 v60, v60
	v_exp_f32_e32 v61, v61
	s_waitcnt lgkmcnt(8)
	v_mfma_f32_32x32x16_bf16 v[18:33], v[114:117], v[90:93], v[18:33]
	v_exp_f32_e32 v62, v62
	v_exp_f32_e32 v63, v63
	v_exp_f32_e32 v64, v64
	v_exp_f32_e32 v65, v65
	s_add_i32 s0, s13, 0x2000
	s_cmpk_lg_i32 s13, 0x4000
	s_cselect_b32 s1, s0, 0
	s_add_i32 s8, s8, 2
	v_lshl_add_u64 v[192:193], v[192:193], 0, s[58:59]
	v_lshl_add_u64 v[194:195], v[194:195], 0, s[58:59]
	s_waitcnt vmcnt(2) lgkmcnt(0)
	s_barrier
	s_andn2_b64 vcc, exec, s[6:7]
	s_cbranch_vccnz .LBB0_515
	s_waitcnt lgkmcnt(0)
	v_add_u32_e32 v94, s11, v218
	ds_read_b128 v[82:85], v94 offset:49248
	ds_read_b128 v[86:89], v94 offset:49216
	ds_read_b128 v[90:93], v94 offset:49152
	ds_read_b128 v[94:97], v94 offset:49184
	s_waitcnt lgkmcnt(3)
	v_pk_mul_f32 v[16:17], v[16:17], v[84:85]
	v_pk_mul_f32 v[14:15], v[14:15], v[82:83]
	s_waitcnt lgkmcnt(2)
	v_pk_mul_f32 v[12:13], v[12:13], v[88:89]
	v_pk_mul_f32 v[10:11], v[10:11], v[86:87]
	s_waitcnt lgkmcnt(0)
	v_pk_mul_f32 v[8:9], v[8:9], v[96:97]
	v_pk_mul_f32 v[6:7], v[6:7], v[94:95]
	v_pk_mul_f32 v[4:5], v[4:5], v[92:93]
	v_pk_mul_f32 v[2:3], v[2:3], v[90:91]
	v_pk_mul_f32 v[32:33], v[32:33], v[84:85]
	v_pk_mul_f32 v[30:31], v[30:31], v[82:83]
	v_pk_mul_f32 v[28:29], v[28:29], v[88:89]
	v_pk_mul_f32 v[26:27], v[26:27], v[86:87]
	v_pk_mul_f32 v[24:25], v[24:25], v[96:97]
	v_pk_mul_f32 v[22:23], v[22:23], v[94:95]
	v_pk_mul_f32 v[20:21], v[20:21], v[92:93]
	v_pk_mul_f32 v[18:19], v[18:19], v[90:91]
.LBB0_515:
	s_cmpk_gt_u32 s8, 0x7c
	s_cbranch_scc1 .LBB0_523
	s_mov_b32 s0, s9
	s_mov_b32 s12, s13
	s_mov_b32 s9, s1
	s_branch .LBB0_509
